# adaLN GEMV slice rewritten: all c/w_ada loads pipelined (56 in flight), same FMA order
# speedup vs baseline: 1.0097x; 1.0006x over previous
.LBB0_22:
	s_mov_b64 s[10:11], s[60:61]
	global_load_dword v100, v18, s[10:11]
	global_load_dword v101, v18, s[10:11] offset:2048
	s_add_u32 s10, s10, 0x1000
	s_addc_u32 s11, s11, 0
	global_load_dword v102, v18, s[10:11]
	global_load_dword v103, v18, s[10:11] offset:2048
	s_add_u32 s10, s10, 0x1000
	s_addc_u32 s11, s11, 0
	global_load_dword v104, v18, s[10:11]
	global_load_dword v105, v18, s[10:11] offset:2048
	s_add_u32 s10, s10, 0x1000
	s_addc_u32 s11, s11, 0
	global_load_dword v106, v18, s[10:11]
	global_load_dword v107, v18, s[10:11] offset:2048
	s_mov_b64 s[10:11], s[62:63]
	global_load_dword v108, v18, s[10:11]
	global_load_dword v109, v18, s[10:11] offset:2048
	s_add_u32 s10, s10, 0x1000
	s_addc_u32 s11, s11, 0
	global_load_dword v110, v18, s[10:11]
	global_load_dword v111, v18, s[10:11] offset:2048
	s_add_u32 s10, s10, 0x1000
	s_addc_u32 s11, s11, 0
	global_load_dword v112, v18, s[10:11]
	global_load_dword v113, v18, s[10:11] offset:2048
	s_add_u32 s10, s10, 0x1000
	s_addc_u32 s11, s11, 0
	global_load_dword v114, v18, s[10:11]
	global_load_dword v115, v18, s[10:11] offset:2048
	s_add_u32 s10, s10, 0x1000
	s_addc_u32 s11, s11, 0
	global_load_dword v116, v18, s[10:11]
	global_load_dword v117, v18, s[10:11] offset:2048
	s_add_u32 s10, s10, 0x1000
	s_addc_u32 s11, s11, 0
	global_load_dword v118, v18, s[10:11]
	global_load_dword v119, v18, s[10:11] offset:2048
	s_add_u32 s10, s10, 0x1000
	s_addc_u32 s11, s11, 0
	global_load_dword v120, v18, s[10:11]
	global_load_dword v121, v18, s[10:11] offset:2048
	s_add_u32 s10, s10, 0x1000
	s_addc_u32 s11, s11, 0
	global_load_dword v122, v18, s[10:11]
	global_load_dword v123, v18, s[10:11] offset:2048
	v_lshlrev_b32_e32 v125, 2, v180
	s_mul_i32 s10, s92, 0x300000
	s_lshl_b32 s11, s6, 2
	s_add_u32 s10, s10, s11
	s_add_u32 s10, s10, s64
	s_addc_u32 s11, s65, 0
	global_load_dword v126, v125, s[10:11]
	s_add_u32 s10, s10, 0x6000
	s_addc_u32 s11, s11, 0
	global_load_dword v127, v125, s[10:11]
	s_add_u32 s10, s10, 0x6000
	s_addc_u32 s11, s11, 0
	global_load_dword v128, v125, s[10:11]
	s_add_u32 s10, s10, 0x6000
	s_addc_u32 s11, s11, 0
	global_load_dword v129, v125, s[10:11]
	s_add_u32 s10, s10, 0x6000
	s_addc_u32 s11, s11, 0
	global_load_dword v130, v125, s[10:11]
	s_add_u32 s10, s10, 0x6000
	s_addc_u32 s11, s11, 0
	global_load_dword v131, v125, s[10:11]
	s_add_u32 s10, s10, 0x6000
	s_addc_u32 s11, s11, 0
	global_load_dword v132, v125, s[10:11]
	s_add_u32 s10, s10, 0x6000
	s_addc_u32 s11, s11, 0
	global_load_dword v133, v125, s[10:11]
	s_add_u32 s10, s10, 0x6000
	s_addc_u32 s11, s11, 0
	global_load_dword v134, v125, s[10:11]
	s_add_u32 s10, s10, 0x6000
	s_addc_u32 s11, s11, 0
	global_load_dword v135, v125, s[10:11]
	s_add_u32 s10, s10, 0x6000
	s_addc_u32 s11, s11, 0
	global_load_dword v136, v125, s[10:11]
	s_add_u32 s10, s10, 0x6000
	s_addc_u32 s11, s11, 0
	global_load_dword v137, v125, s[10:11]
	s_add_u32 s10, s10, 0x6000
	s_addc_u32 s11, s11, 0
	global_load_dword v138, v125, s[10:11]
	s_add_u32 s10, s10, 0x6000
	s_addc_u32 s11, s11, 0
	global_load_dword v139, v125, s[10:11]
	s_add_u32 s10, s10, 0x6000
	s_addc_u32 s11, s11, 0
	global_load_dword v140, v125, s[10:11]
	s_add_u32 s10, s10, 0x6000
	s_addc_u32 s11, s11, 0
	global_load_dword v141, v125, s[10:11]
	s_add_u32 s10, s10, 0x6000
	s_addc_u32 s11, s11, 0
	global_load_dword v142, v125, s[10:11]
	s_add_u32 s10, s10, 0x6000
	s_addc_u32 s11, s11, 0
	global_load_dword v143, v125, s[10:11]
	s_add_u32 s10, s10, 0x6000
	s_addc_u32 s11, s11, 0
	global_load_dword v144, v125, s[10:11]
	s_add_u32 s10, s10, 0x6000
	s_addc_u32 s11, s11, 0
	global_load_dword v145, v125, s[10:11]
	s_add_u32 s10, s10, 0x6000
	s_addc_u32 s11, s11, 0
	global_load_dword v146, v125, s[10:11]
	s_add_u32 s10, s10, 0x6000
	s_addc_u32 s11, s11, 0
	global_load_dword v147, v125, s[10:11]
	s_add_u32 s10, s10, 0x6000
	s_addc_u32 s11, s11, 0
	global_load_dword v148, v125, s[10:11]
	s_add_u32 s10, s10, 0x6000
	s_addc_u32 s11, s11, 0
	global_load_dword v149, v125, s[10:11]
	s_add_u32 s10, s10, 0x6000
	s_addc_u32 s11, s11, 0
	global_load_dword v150, v125, s[10:11]
	s_add_u32 s10, s10, 0x6000
	s_addc_u32 s11, s11, 0
	global_load_dword v151, v125, s[10:11]
	s_add_u32 s10, s10, 0x6000
	s_addc_u32 s11, s11, 0
	global_load_dword v152, v125, s[10:11]
	s_add_u32 s10, s10, 0x6000
	s_addc_u32 s11, s11, 0
	global_load_dword v153, v125, s[10:11]
	s_add_u32 s10, s10, 0x6000
	s_addc_u32 s11, s11, 0
	global_load_dword v154, v125, s[10:11]
	s_add_u32 s10, s10, 0x6000
	s_addc_u32 s11, s11, 0
	global_load_dword v155, v125, s[10:11]
	s_add_u32 s10, s10, 0x6000
	s_addc_u32 s11, s11, 0
	global_load_dword v156, v125, s[10:11]
	s_add_u32 s10, s10, 0x6000
	s_addc_u32 s11, s11, 0
	global_load_dword v157, v125, s[10:11]
	s_add_u32 s10, s10, 0x6000
	s_addc_u32 s11, s11, 0
	s_waitcnt vmcnt(55)
	v_mul_f32_e32 v6, 0xbfb8aa3b, v100
	v_exp_f32_e32 v6, v6
	s_nop 0
	v_add_f32_e32 v6, 1.0, v6
	v_div_scale_f32 v7, s[8:9], v6, v6, v100
	v_rcp_f32_e32 v8, v7
	v_div_scale_f32 v9, vcc, v100, v6, v100
	v_fma_f32 v10, -v7, v8, 1.0
	v_fmac_f32_e32 v8, v10, v8
	v_mul_f32_e32 v10, v9, v8
	v_fma_f32 v11, -v7, v10, v9
	v_fmac_f32_e32 v10, v11, v8
	v_fma_f32 v7, -v7, v10, v9
	v_div_fmas_f32 v7, v7, v8, v10
	v_div_fixup_f32 v0, v7, v6, v100
	ds_write_b32 v18, v0
	s_waitcnt vmcnt(54)
	v_mul_f32_e32 v6, 0xbfb8aa3b, v101
	v_exp_f32_e32 v6, v6
	s_nop 0
	v_add_f32_e32 v6, 1.0, v6
	v_div_scale_f32 v7, s[8:9], v6, v6, v101
	v_rcp_f32_e32 v8, v7
	v_div_scale_f32 v9, vcc, v101, v6, v101
	v_fma_f32 v10, -v7, v8, 1.0
	v_fmac_f32_e32 v8, v10, v8
	v_mul_f32_e32 v10, v9, v8
	v_fma_f32 v11, -v7, v10, v9
	v_fmac_f32_e32 v10, v11, v8
	v_fma_f32 v7, -v7, v10, v9
	v_div_fmas_f32 v7, v7, v8, v10
	v_div_fixup_f32 v0, v7, v6, v101
	ds_write_b32 v18, v0 offset:2048
	s_waitcnt vmcnt(53)
	v_mul_f32_e32 v6, 0xbfb8aa3b, v102
	v_exp_f32_e32 v6, v6
	s_nop 0
	v_add_f32_e32 v6, 1.0, v6
	v_div_scale_f32 v7, s[8:9], v6, v6, v102
	v_rcp_f32_e32 v8, v7
	v_div_scale_f32 v9, vcc, v102, v6, v102
	v_fma_f32 v10, -v7, v8, 1.0
	v_fmac_f32_e32 v8, v10, v8
	v_mul_f32_e32 v10, v9, v8
	v_fma_f32 v11, -v7, v10, v9
	v_fmac_f32_e32 v10, v11, v8
	v_fma_f32 v7, -v7, v10, v9
	v_div_fmas_f32 v7, v7, v8, v10
	v_div_fixup_f32 v0, v7, v6, v102
	ds_write_b32 v18, v0 offset:4096
	s_waitcnt vmcnt(52)
	v_mul_f32_e32 v6, 0xbfb8aa3b, v103
	v_exp_f32_e32 v6, v6
	s_nop 0
	v_add_f32_e32 v6, 1.0, v6
	v_div_scale_f32 v7, s[8:9], v6, v6, v103
	v_rcp_f32_e32 v8, v7
	v_div_scale_f32 v9, vcc, v103, v6, v103
	v_fma_f32 v10, -v7, v8, 1.0
	v_fmac_f32_e32 v8, v10, v8
	v_mul_f32_e32 v10, v9, v8
	v_fma_f32 v11, -v7, v10, v9
	v_fmac_f32_e32 v10, v11, v8
	v_fma_f32 v7, -v7, v10, v9
	v_div_fmas_f32 v7, v7, v8, v10
	v_div_fixup_f32 v0, v7, v6, v103
	ds_write_b32 v18, v0 offset:6144
	s_waitcnt vmcnt(51)
	v_mul_f32_e32 v6, 0xbfb8aa3b, v104
	v_exp_f32_e32 v6, v6
	s_nop 0
	v_add_f32_e32 v6, 1.0, v6
	v_div_scale_f32 v7, s[8:9], v6, v6, v104
	v_rcp_f32_e32 v8, v7
	v_div_scale_f32 v9, vcc, v104, v6, v104
	v_fma_f32 v10, -v7, v8, 1.0
	v_fmac_f32_e32 v8, v10, v8
	v_mul_f32_e32 v10, v9, v8
	v_fma_f32 v11, -v7, v10, v9
	v_fmac_f32_e32 v10, v11, v8
	v_fma_f32 v7, -v7, v10, v9
	v_div_fmas_f32 v7, v7, v8, v10
	v_div_fixup_f32 v0, v7, v6, v104
	ds_write_b32 v18, v0 offset:8192
	s_waitcnt vmcnt(50)
	v_mul_f32_e32 v6, 0xbfb8aa3b, v105
	v_exp_f32_e32 v6, v6
	s_nop 0
	v_add_f32_e32 v6, 1.0, v6
	v_div_scale_f32 v7, s[8:9], v6, v6, v105
	v_rcp_f32_e32 v8, v7
	v_div_scale_f32 v9, vcc, v105, v6, v105
	v_fma_f32 v10, -v7, v8, 1.0
	v_fmac_f32_e32 v8, v10, v8
	v_mul_f32_e32 v10, v9, v8
	v_fma_f32 v11, -v7, v10, v9
	v_fmac_f32_e32 v10, v11, v8
	v_fma_f32 v7, -v7, v10, v9
	v_div_fmas_f32 v7, v7, v8, v10
	v_div_fixup_f32 v0, v7, v6, v105
	ds_write_b32 v18, v0 offset:10240
	s_waitcnt vmcnt(49)
	v_mul_f32_e32 v6, 0xbfb8aa3b, v106
	v_exp_f32_e32 v6, v6
	s_nop 0
	v_add_f32_e32 v6, 1.0, v6
	v_div_scale_f32 v7, s[8:9], v6, v6, v106
	v_rcp_f32_e32 v8, v7
	v_div_scale_f32 v9, vcc, v106, v6, v106
	v_fma_f32 v10, -v7, v8, 1.0
	v_fmac_f32_e32 v8, v10, v8
	v_mul_f32_e32 v10, v9, v8
	v_fma_f32 v11, -v7, v10, v9
	v_fmac_f32_e32 v10, v11, v8
	v_fma_f32 v7, -v7, v10, v9
	v_div_fmas_f32 v7, v7, v8, v10
	v_div_fixup_f32 v0, v7, v6, v106
	ds_write_b32 v18, v0 offset:12288
	s_waitcnt vmcnt(48)
	v_mul_f32_e32 v6, 0xbfb8aa3b, v107
	v_exp_f32_e32 v6, v6
	s_nop 0
	v_add_f32_e32 v6, 1.0, v6
	v_div_scale_f32 v7, s[8:9], v6, v6, v107
	v_rcp_f32_e32 v8, v7
	v_div_scale_f32 v9, vcc, v107, v6, v107
	v_fma_f32 v10, -v7, v8, 1.0
	v_fmac_f32_e32 v8, v10, v8
	v_mul_f32_e32 v10, v9, v8
	v_fma_f32 v11, -v7, v10, v9
	v_fmac_f32_e32 v10, v11, v8
	v_fma_f32 v7, -v7, v10, v9
	v_div_fmas_f32 v7, v7, v8, v10
	v_div_fixup_f32 v0, v7, v6, v107
	ds_write_b32 v18, v0 offset:14336
	s_waitcnt vmcnt(47)
	v_mul_f32_e32 v6, 0xbfb8aa3b, v108
	v_exp_f32_e32 v6, v6
	s_nop 0
	v_add_f32_e32 v6, 1.0, v6
	v_div_scale_f32 v7, s[8:9], v6, v6, v108
	v_rcp_f32_e32 v8, v7
	v_div_scale_f32 v9, vcc, v108, v6, v108
	v_fma_f32 v10, -v7, v8, 1.0
	v_fmac_f32_e32 v8, v10, v8
	v_mul_f32_e32 v10, v9, v8
	v_fma_f32 v11, -v7, v10, v9
	v_fmac_f32_e32 v10, v11, v8
	v_fma_f32 v7, -v7, v10, v9
	v_div_fmas_f32 v7, v7, v8, v10
	v_div_fixup_f32 v0, v7, v6, v108
	ds_write_b32 v18, v0 offset:16384
	s_waitcnt vmcnt(46)
	v_mul_f32_e32 v6, 0xbfb8aa3b, v109
	v_exp_f32_e32 v6, v6
	s_nop 0
	v_add_f32_e32 v6, 1.0, v6
	v_div_scale_f32 v7, s[8:9], v6, v6, v109
	v_rcp_f32_e32 v8, v7
	v_div_scale_f32 v9, vcc, v109, v6, v109
	v_fma_f32 v10, -v7, v8, 1.0
	v_fmac_f32_e32 v8, v10, v8
	v_mul_f32_e32 v10, v9, v8
	v_fma_f32 v11, -v7, v10, v9
	v_fmac_f32_e32 v10, v11, v8
	v_fma_f32 v7, -v7, v10, v9
	v_div_fmas_f32 v7, v7, v8, v10
	v_div_fixup_f32 v0, v7, v6, v109
	ds_write_b32 v18, v0 offset:18432
	s_waitcnt vmcnt(45)
	v_mul_f32_e32 v6, 0xbfb8aa3b, v110
	v_exp_f32_e32 v6, v6
	s_nop 0
	v_add_f32_e32 v6, 1.0, v6
	v_div_scale_f32 v7, s[8:9], v6, v6, v110
	v_rcp_f32_e32 v8, v7
	v_div_scale_f32 v9, vcc, v110, v6, v110
	v_fma_f32 v10, -v7, v8, 1.0
	v_fmac_f32_e32 v8, v10, v8
	v_mul_f32_e32 v10, v9, v8
	v_fma_f32 v11, -v7, v10, v9
	v_fmac_f32_e32 v10, v11, v8
	v_fma_f32 v7, -v7, v10, v9
	v_div_fmas_f32 v7, v7, v8, v10
	v_div_fixup_f32 v0, v7, v6, v110
	ds_write_b32 v18, v0 offset:20480
	s_waitcnt vmcnt(44)
	v_mul_f32_e32 v6, 0xbfb8aa3b, v111
	v_exp_f32_e32 v6, v6
	s_nop 0
	v_add_f32_e32 v6, 1.0, v6
	v_div_scale_f32 v7, s[8:9], v6, v6, v111
	v_rcp_f32_e32 v8, v7
	v_div_scale_f32 v9, vcc, v111, v6, v111
	v_fma_f32 v10, -v7, v8, 1.0
	v_fmac_f32_e32 v8, v10, v8
	v_mul_f32_e32 v10, v9, v8
	v_fma_f32 v11, -v7, v10, v9
	v_fmac_f32_e32 v10, v11, v8
	v_fma_f32 v7, -v7, v10, v9
	v_div_fmas_f32 v7, v7, v8, v10
	v_div_fixup_f32 v0, v7, v6, v111
	ds_write_b32 v18, v0 offset:22528
	s_waitcnt vmcnt(43)
	v_mul_f32_e32 v6, 0xbfb8aa3b, v112
	v_exp_f32_e32 v6, v6
	s_nop 0
	v_add_f32_e32 v6, 1.0, v6
	v_div_scale_f32 v7, s[8:9], v6, v6, v112
	v_rcp_f32_e32 v8, v7
	v_div_scale_f32 v9, vcc, v112, v6, v112
	v_fma_f32 v10, -v7, v8, 1.0
	v_fmac_f32_e32 v8, v10, v8
	v_mul_f32_e32 v10, v9, v8
	v_fma_f32 v11, -v7, v10, v9
	v_fmac_f32_e32 v10, v11, v8
	v_fma_f32 v7, -v7, v10, v9
	v_div_fmas_f32 v7, v7, v8, v10
	v_div_fixup_f32 v0, v7, v6, v112
	ds_write_b32 v18, v0 offset:24576
	s_waitcnt vmcnt(42)
	v_mul_f32_e32 v6, 0xbfb8aa3b, v113
	v_exp_f32_e32 v6, v6
	s_nop 0
	v_add_f32_e32 v6, 1.0, v6
	v_div_scale_f32 v7, s[8:9], v6, v6, v113
	v_rcp_f32_e32 v8, v7
	v_div_scale_f32 v9, vcc, v113, v6, v113
	v_fma_f32 v10, -v7, v8, 1.0
	v_fmac_f32_e32 v8, v10, v8
	v_mul_f32_e32 v10, v9, v8
	v_fma_f32 v11, -v7, v10, v9
	v_fmac_f32_e32 v10, v11, v8
	v_fma_f32 v7, -v7, v10, v9
	v_div_fmas_f32 v7, v7, v8, v10
	v_div_fixup_f32 v0, v7, v6, v113
	ds_write_b32 v18, v0 offset:26624
	s_waitcnt vmcnt(41)
	v_mul_f32_e32 v6, 0xbfb8aa3b, v114
	v_exp_f32_e32 v6, v6
	s_nop 0
	v_add_f32_e32 v6, 1.0, v6
	v_div_scale_f32 v7, s[8:9], v6, v6, v114
	v_rcp_f32_e32 v8, v7
	v_div_scale_f32 v9, vcc, v114, v6, v114
	v_fma_f32 v10, -v7, v8, 1.0
	v_fmac_f32_e32 v8, v10, v8
	v_mul_f32_e32 v10, v9, v8
	v_fma_f32 v11, -v7, v10, v9
	v_fmac_f32_e32 v10, v11, v8
	v_fma_f32 v7, -v7, v10, v9
	v_div_fmas_f32 v7, v7, v8, v10
	v_div_fixup_f32 v0, v7, v6, v114
	ds_write_b32 v18, v0 offset:28672
	s_waitcnt vmcnt(40)
	v_mul_f32_e32 v6, 0xbfb8aa3b, v115
	v_exp_f32_e32 v6, v6
	s_nop 0
	v_add_f32_e32 v6, 1.0, v6
	v_div_scale_f32 v7, s[8:9], v6, v6, v115
	v_rcp_f32_e32 v8, v7
	v_div_scale_f32 v9, vcc, v115, v6, v115
	v_fma_f32 v10, -v7, v8, 1.0
	v_fmac_f32_e32 v8, v10, v8
	v_mul_f32_e32 v10, v9, v8
	v_fma_f32 v11, -v7, v10, v9
	v_fmac_f32_e32 v10, v11, v8
	v_fma_f32 v7, -v7, v10, v9
	v_div_fmas_f32 v7, v7, v8, v10
	v_div_fixup_f32 v0, v7, v6, v115
	ds_write_b32 v18, v0 offset:30720
	s_waitcnt vmcnt(39)
	v_mul_f32_e32 v6, 0xbfb8aa3b, v116
	v_exp_f32_e32 v6, v6
	s_nop 0
	v_add_f32_e32 v6, 1.0, v6
	v_div_scale_f32 v7, s[8:9], v6, v6, v116
	v_rcp_f32_e32 v8, v7
	v_div_scale_f32 v9, vcc, v116, v6, v116
	v_fma_f32 v10, -v7, v8, 1.0
	v_fmac_f32_e32 v8, v10, v8
	v_mul_f32_e32 v10, v9, v8
	v_fma_f32 v11, -v7, v10, v9
	v_fmac_f32_e32 v10, v11, v8
	v_fma_f32 v7, -v7, v10, v9
	v_div_fmas_f32 v7, v7, v8, v10
	v_div_fixup_f32 v0, v7, v6, v116
	ds_write_b32 v18, v0 offset:32768
	s_waitcnt vmcnt(38)
	v_mul_f32_e32 v6, 0xbfb8aa3b, v117
	v_exp_f32_e32 v6, v6
	s_nop 0
	v_add_f32_e32 v6, 1.0, v6
	v_div_scale_f32 v7, s[8:9], v6, v6, v117
	v_rcp_f32_e32 v8, v7
	v_div_scale_f32 v9, vcc, v117, v6, v117
	v_fma_f32 v10, -v7, v8, 1.0
	v_fmac_f32_e32 v8, v10, v8
	v_mul_f32_e32 v10, v9, v8
	v_fma_f32 v11, -v7, v10, v9
	v_fmac_f32_e32 v10, v11, v8
	v_fma_f32 v7, -v7, v10, v9
	v_div_fmas_f32 v7, v7, v8, v10
	v_div_fixup_f32 v0, v7, v6, v117
	ds_write_b32 v18, v0 offset:34816
	s_waitcnt vmcnt(37)
	v_mul_f32_e32 v6, 0xbfb8aa3b, v118
	v_exp_f32_e32 v6, v6
	s_nop 0
	v_add_f32_e32 v6, 1.0, v6
	v_div_scale_f32 v7, s[8:9], v6, v6, v118
	v_rcp_f32_e32 v8, v7
	v_div_scale_f32 v9, vcc, v118, v6, v118
	v_fma_f32 v10, -v7, v8, 1.0
	v_fmac_f32_e32 v8, v10, v8
	v_mul_f32_e32 v10, v9, v8
	v_fma_f32 v11, -v7, v10, v9
	v_fmac_f32_e32 v10, v11, v8
	v_fma_f32 v7, -v7, v10, v9
	v_div_fmas_f32 v7, v7, v8, v10
	v_div_fixup_f32 v0, v7, v6, v118
	ds_write_b32 v18, v0 offset:36864
	s_waitcnt vmcnt(36)
	v_mul_f32_e32 v6, 0xbfb8aa3b, v119
	v_exp_f32_e32 v6, v6
	s_nop 0
	v_add_f32_e32 v6, 1.0, v6
	v_div_scale_f32 v7, s[8:9], v6, v6, v119
	v_rcp_f32_e32 v8, v7
	v_div_scale_f32 v9, vcc, v119, v6, v119
	v_fma_f32 v10, -v7, v8, 1.0
	v_fmac_f32_e32 v8, v10, v8
	v_mul_f32_e32 v10, v9, v8
	v_fma_f32 v11, -v7, v10, v9
	v_fmac_f32_e32 v10, v11, v8
	v_fma_f32 v7, -v7, v10, v9
	v_div_fmas_f32 v7, v7, v8, v10
	v_div_fixup_f32 v0, v7, v6, v119
	ds_write_b32 v18, v0 offset:38912
	s_waitcnt vmcnt(35)
	v_mul_f32_e32 v6, 0xbfb8aa3b, v120
	v_exp_f32_e32 v6, v6
	s_nop 0
	v_add_f32_e32 v6, 1.0, v6
	v_div_scale_f32 v7, s[8:9], v6, v6, v120
	v_rcp_f32_e32 v8, v7
	v_div_scale_f32 v9, vcc, v120, v6, v120
	v_fma_f32 v10, -v7, v8, 1.0
	v_fmac_f32_e32 v8, v10, v8
	v_mul_f32_e32 v10, v9, v8
	v_fma_f32 v11, -v7, v10, v9
	v_fmac_f32_e32 v10, v11, v8
	v_fma_f32 v7, -v7, v10, v9
	v_div_fmas_f32 v7, v7, v8, v10
	v_div_fixup_f32 v0, v7, v6, v120
	ds_write_b32 v18, v0 offset:40960
	s_waitcnt vmcnt(34)
	v_mul_f32_e32 v6, 0xbfb8aa3b, v121
	v_exp_f32_e32 v6, v6
	s_nop 0
	v_add_f32_e32 v6, 1.0, v6
	v_div_scale_f32 v7, s[8:9], v6, v6, v121
	v_rcp_f32_e32 v8, v7
	v_div_scale_f32 v9, vcc, v121, v6, v121
	v_fma_f32 v10, -v7, v8, 1.0
	v_fmac_f32_e32 v8, v10, v8
	v_mul_f32_e32 v10, v9, v8
	v_fma_f32 v11, -v7, v10, v9
	v_fmac_f32_e32 v10, v11, v8
	v_fma_f32 v7, -v7, v10, v9
	v_div_fmas_f32 v7, v7, v8, v10
	v_div_fixup_f32 v0, v7, v6, v121
	ds_write_b32 v18, v0 offset:43008
	s_waitcnt vmcnt(33)
	v_mul_f32_e32 v6, 0xbfb8aa3b, v122
	v_exp_f32_e32 v6, v6
	s_nop 0
	v_add_f32_e32 v6, 1.0, v6
	v_div_scale_f32 v7, s[8:9], v6, v6, v122
	v_rcp_f32_e32 v8, v7
	v_div_scale_f32 v9, vcc, v122, v6, v122
	v_fma_f32 v10, -v7, v8, 1.0
	v_fmac_f32_e32 v8, v10, v8
	v_mul_f32_e32 v10, v9, v8
	v_fma_f32 v11, -v7, v10, v9
	v_fmac_f32_e32 v10, v11, v8
	v_fma_f32 v7, -v7, v10, v9
	v_div_fmas_f32 v7, v7, v8, v10
	v_div_fixup_f32 v0, v7, v6, v122
	ds_write_b32 v18, v0 offset:45056
	s_waitcnt vmcnt(32)
	v_mul_f32_e32 v6, 0xbfb8aa3b, v123
	v_exp_f32_e32 v6, v6
	s_nop 0
	v_add_f32_e32 v6, 1.0, v6
	v_div_scale_f32 v7, s[8:9], v6, v6, v123
	v_rcp_f32_e32 v8, v7
	v_div_scale_f32 v9, vcc, v123, v6, v123
	v_fma_f32 v10, -v7, v8, 1.0
	v_fmac_f32_e32 v8, v10, v8
	v_mul_f32_e32 v10, v9, v8
	v_fma_f32 v11, -v7, v10, v9
	v_fmac_f32_e32 v10, v11, v8
	v_fma_f32 v7, -v7, v10, v9
	v_div_fmas_f32 v7, v7, v8, v10
	v_div_fixup_f32 v0, v7, v6, v123
	ds_write_b32 v18, v0 offset:47104
	v_mov_b32_e32 v6, 0
	v_mov_b32_e32 v7, 0
	v_mov_b32_e32 v8, 0
	v_mov_b32_e32 v9, 0
	v_mov_b32_e32 v10, 0
	v_mov_b32_e32 v11, 0
	v_mov_b32_e32 v12, 0
	v_mov_b32_e32 v13, 0
	v_mov_b32_e32 v14, 0
	v_mov_b32_e32 v15, 0
	v_mov_b32_e32 v16, 0
	v_mov_b32_e32 v17, 0
	v_mov_b32_e32 v27, s14
	s_waitcnt lgkmcnt(0)
	s_barrier
	s_mov_b32 s8, 3
.Lada_loop:
	ds_read_b128 v[28:31], v27 offset:0
	ds_read_b128 v[32:35], v27 offset:4096
	ds_read_b128 v[36:39], v27 offset:8192
	ds_read_b128 v[40:43], v27 offset:12288
	ds_read_b128 v[44:47], v27 offset:16384
	ds_read_b128 v[48:51], v27 offset:20480
	ds_read_b128 v[52:55], v27 offset:24576
	ds_read_b128 v[56:59], v27 offset:28672
	ds_read_b128 v[60:63], v27 offset:32768
	ds_read_b128 v[64:67], v27 offset:36864
	ds_read_b128 v[68:71], v27 offset:40960
	ds_read_b128 v[72:75], v27 offset:45056
	ds_read_b128 v[182:185], v27 offset:16
	ds_read_b128 v[186:189], v27 offset:4112
	ds_read_b128 v[190:193], v27 offset:8208
	ds_read_b128 v[194:197], v27 offset:12304
	ds_read_b128 v[198:201], v27 offset:16400
	ds_read_b128 v[202:205], v27 offset:20496
	ds_read_b128 v[206:209], v27 offset:24592
	ds_read_b128 v[210:213], v27 offset:28688
	ds_read_b128 v[214:217], v27 offset:32784
	ds_read_b128 v[218:221], v27 offset:36880
	ds_read_b128 v[222:225], v27 offset:40976
	ds_read_b128 v[226:229], v27 offset:45072
	s_waitcnt vmcnt(28)
	s_waitcnt lgkmcnt(12)
	v_fmac_f32_e32 v8, v126, v28
	v_fmac_f32_e32 v9, v126, v32
	v_fmac_f32_e32 v10, v126, v36
	v_fmac_f32_e32 v11, v126, v40
	v_fmac_f32_e32 v12, v126, v44
	v_fmac_f32_e32 v13, v126, v48
	v_fmac_f32_e32 v14, v126, v52
	v_fmac_f32_e32 v15, v126, v56
	v_fmac_f32_e32 v16, v126, v60
	v_fmac_f32_e32 v17, v126, v64
	v_fmac_f32_e32 v6, v126, v68
	v_fmac_f32_e32 v7, v126, v72
	v_fmac_f32_e32 v8, v127, v29
	v_fmac_f32_e32 v9, v127, v33
	v_fmac_f32_e32 v10, v127, v37
	v_fmac_f32_e32 v11, v127, v41
	v_fmac_f32_e32 v12, v127, v45
	v_fmac_f32_e32 v13, v127, v49
	v_fmac_f32_e32 v14, v127, v53
	v_fmac_f32_e32 v15, v127, v57
	v_fmac_f32_e32 v16, v127, v61
	v_fmac_f32_e32 v17, v127, v65
	v_fmac_f32_e32 v6, v127, v69
	v_fmac_f32_e32 v7, v127, v73
	v_fmac_f32_e32 v8, v128, v30
	v_fmac_f32_e32 v9, v128, v34
	v_fmac_f32_e32 v10, v128, v38
	v_fmac_f32_e32 v11, v128, v42
	v_fmac_f32_e32 v12, v128, v46
	v_fmac_f32_e32 v13, v128, v50
	v_fmac_f32_e32 v14, v128, v54
	v_fmac_f32_e32 v15, v128, v58
	v_fmac_f32_e32 v16, v128, v62
	v_fmac_f32_e32 v17, v128, v66
	v_fmac_f32_e32 v6, v128, v70
	v_fmac_f32_e32 v7, v128, v74
	v_fmac_f32_e32 v8, v129, v31
	v_fmac_f32_e32 v9, v129, v35
	v_fmac_f32_e32 v10, v129, v39
	v_fmac_f32_e32 v11, v129, v43
	v_fmac_f32_e32 v12, v129, v47
	v_fmac_f32_e32 v13, v129, v51
	v_fmac_f32_e32 v14, v129, v55
	v_fmac_f32_e32 v15, v129, v59
	v_fmac_f32_e32 v16, v129, v63
	v_fmac_f32_e32 v17, v129, v67
	v_fmac_f32_e32 v6, v129, v71
	v_fmac_f32_e32 v7, v129, v75
	ds_read_b128 v[28:31], v27 offset:32
	ds_read_b128 v[32:35], v27 offset:4128
	ds_read_b128 v[36:39], v27 offset:8224
	ds_read_b128 v[40:43], v27 offset:12320
	ds_read_b128 v[44:47], v27 offset:16416
	ds_read_b128 v[48:51], v27 offset:20512
	ds_read_b128 v[52:55], v27 offset:24608
	ds_read_b128 v[56:59], v27 offset:28704
	ds_read_b128 v[60:63], v27 offset:32800
	ds_read_b128 v[64:67], v27 offset:36896
	ds_read_b128 v[68:71], v27 offset:40992
	ds_read_b128 v[72:75], v27 offset:45088
	s_waitcnt vmcnt(24)
	s_waitcnt lgkmcnt(12)
	v_fmac_f32_e32 v8, v130, v182
	v_fmac_f32_e32 v9, v130, v186
	v_fmac_f32_e32 v10, v130, v190
	v_fmac_f32_e32 v11, v130, v194
	v_fmac_f32_e32 v12, v130, v198
	v_fmac_f32_e32 v13, v130, v202
	v_fmac_f32_e32 v14, v130, v206
	v_fmac_f32_e32 v15, v130, v210
	v_fmac_f32_e32 v16, v130, v214
	v_fmac_f32_e32 v17, v130, v218
	v_fmac_f32_e32 v6, v130, v222
	v_fmac_f32_e32 v7, v130, v226
	v_fmac_f32_e32 v8, v131, v183
	v_fmac_f32_e32 v9, v131, v187
	v_fmac_f32_e32 v10, v131, v191
	v_fmac_f32_e32 v11, v131, v195
	v_fmac_f32_e32 v12, v131, v199
	v_fmac_f32_e32 v13, v131, v203
	v_fmac_f32_e32 v14, v131, v207
	v_fmac_f32_e32 v15, v131, v211
	v_fmac_f32_e32 v16, v131, v215
	v_fmac_f32_e32 v17, v131, v219
	v_fmac_f32_e32 v6, v131, v223
	v_fmac_f32_e32 v7, v131, v227
	v_fmac_f32_e32 v8, v132, v184
	v_fmac_f32_e32 v9, v132, v188
	v_fmac_f32_e32 v10, v132, v192
	v_fmac_f32_e32 v11, v132, v196
	v_fmac_f32_e32 v12, v132, v200
	v_fmac_f32_e32 v13, v132, v204
	v_fmac_f32_e32 v14, v132, v208
	v_fmac_f32_e32 v15, v132, v212
	v_fmac_f32_e32 v16, v132, v216
	v_fmac_f32_e32 v17, v132, v220
	v_fmac_f32_e32 v6, v132, v224
	v_fmac_f32_e32 v7, v132, v228
	v_fmac_f32_e32 v8, v133, v185
	v_fmac_f32_e32 v9, v133, v189
	v_fmac_f32_e32 v10, v133, v193
	v_fmac_f32_e32 v11, v133, v197
	v_fmac_f32_e32 v12, v133, v201
	v_fmac_f32_e32 v13, v133, v205
	v_fmac_f32_e32 v14, v133, v209
	v_fmac_f32_e32 v15, v133, v213
	v_fmac_f32_e32 v16, v133, v217
	v_fmac_f32_e32 v17, v133, v221
	v_fmac_f32_e32 v6, v133, v225
	v_fmac_f32_e32 v7, v133, v229
	ds_read_b128 v[182:185], v27 offset:48
	ds_read_b128 v[186:189], v27 offset:4144
	ds_read_b128 v[190:193], v27 offset:8240
	ds_read_b128 v[194:197], v27 offset:12336
	ds_read_b128 v[198:201], v27 offset:16432
	ds_read_b128 v[202:205], v27 offset:20528
	ds_read_b128 v[206:209], v27 offset:24624
	ds_read_b128 v[210:213], v27 offset:28720
	ds_read_b128 v[214:217], v27 offset:32816
	ds_read_b128 v[218:221], v27 offset:36912
	ds_read_b128 v[222:225], v27 offset:41008
	ds_read_b128 v[226:229], v27 offset:45104
	s_waitcnt vmcnt(20)
	s_waitcnt lgkmcnt(12)
	v_fmac_f32_e32 v8, v134, v28
	v_fmac_f32_e32 v9, v134, v32
	v_fmac_f32_e32 v10, v134, v36
	v_fmac_f32_e32 v11, v134, v40
	v_fmac_f32_e32 v12, v134, v44
	v_fmac_f32_e32 v13, v134, v48
	v_fmac_f32_e32 v14, v134, v52
	v_fmac_f32_e32 v15, v134, v56
	v_fmac_f32_e32 v16, v134, v60
	v_fmac_f32_e32 v17, v134, v64
	v_fmac_f32_e32 v6, v134, v68
	v_fmac_f32_e32 v7, v134, v72
	v_fmac_f32_e32 v8, v135, v29
	v_fmac_f32_e32 v9, v135, v33
	v_fmac_f32_e32 v10, v135, v37
	v_fmac_f32_e32 v11, v135, v41
	v_fmac_f32_e32 v12, v135, v45
	v_fmac_f32_e32 v13, v135, v49
	v_fmac_f32_e32 v14, v135, v53
	v_fmac_f32_e32 v15, v135, v57
	v_fmac_f32_e32 v16, v135, v61
	v_fmac_f32_e32 v17, v135, v65
	v_fmac_f32_e32 v6, v135, v69
	v_fmac_f32_e32 v7, v135, v73
	v_fmac_f32_e32 v8, v136, v30
	v_fmac_f32_e32 v9, v136, v34
	v_fmac_f32_e32 v10, v136, v38
	v_fmac_f32_e32 v11, v136, v42
	v_fmac_f32_e32 v12, v136, v46
	v_fmac_f32_e32 v13, v136, v50
	v_fmac_f32_e32 v14, v136, v54
	v_fmac_f32_e32 v15, v136, v58
	v_fmac_f32_e32 v16, v136, v62
	v_fmac_f32_e32 v17, v136, v66
	v_fmac_f32_e32 v6, v136, v70
	v_fmac_f32_e32 v7, v136, v74
	v_fmac_f32_e32 v8, v137, v31
	v_fmac_f32_e32 v9, v137, v35
	v_fmac_f32_e32 v10, v137, v39
	v_fmac_f32_e32 v11, v137, v43
	v_fmac_f32_e32 v12, v137, v47
	v_fmac_f32_e32 v13, v137, v51
	v_fmac_f32_e32 v14, v137, v55
	v_fmac_f32_e32 v15, v137, v59
	v_fmac_f32_e32 v16, v137, v63
	v_fmac_f32_e32 v17, v137, v67
	v_fmac_f32_e32 v6, v137, v71
	v_fmac_f32_e32 v7, v137, v75
	s_waitcnt vmcnt(16)
	s_waitcnt lgkmcnt(0)
	v_fmac_f32_e32 v8, v138, v182
	v_fmac_f32_e32 v9, v138, v186
	v_fmac_f32_e32 v10, v138, v190
	v_fmac_f32_e32 v11, v138, v194
	v_fmac_f32_e32 v12, v138, v198
	v_fmac_f32_e32 v13, v138, v202
	v_fmac_f32_e32 v14, v138, v206
	v_fmac_f32_e32 v15, v138, v210
	v_fmac_f32_e32 v16, v138, v214
	v_fmac_f32_e32 v17, v138, v218
	v_fmac_f32_e32 v6, v138, v222
	v_fmac_f32_e32 v7, v138, v226
	v_fmac_f32_e32 v8, v139, v183
	v_fmac_f32_e32 v9, v139, v187
	v_fmac_f32_e32 v10, v139, v191
	v_fmac_f32_e32 v11, v139, v195
	v_fmac_f32_e32 v12, v139, v199
	v_fmac_f32_e32 v13, v139, v203
	v_fmac_f32_e32 v14, v139, v207
	v_fmac_f32_e32 v15, v139, v211
	v_fmac_f32_e32 v16, v139, v215
	v_fmac_f32_e32 v17, v139, v219
	v_fmac_f32_e32 v6, v139, v223
	v_fmac_f32_e32 v7, v139, v227
	v_fmac_f32_e32 v8, v140, v184
	v_fmac_f32_e32 v9, v140, v188
	v_fmac_f32_e32 v10, v140, v192
	v_fmac_f32_e32 v11, v140, v196
	v_fmac_f32_e32 v12, v140, v200
	v_fmac_f32_e32 v13, v140, v204
	v_fmac_f32_e32 v14, v140, v208
	v_fmac_f32_e32 v15, v140, v212
	v_fmac_f32_e32 v16, v140, v216
	v_fmac_f32_e32 v17, v140, v220
	v_fmac_f32_e32 v6, v140, v224
	v_fmac_f32_e32 v7, v140, v228
	v_fmac_f32_e32 v8, v141, v185
	v_fmac_f32_e32 v9, v141, v189
	v_fmac_f32_e32 v10, v141, v193
	v_fmac_f32_e32 v11, v141, v197
	v_fmac_f32_e32 v12, v141, v201
	v_fmac_f32_e32 v13, v141, v205
	v_fmac_f32_e32 v14, v141, v209
	v_fmac_f32_e32 v15, v141, v213
	v_fmac_f32_e32 v16, v141, v217
	v_fmac_f32_e32 v17, v141, v221
	v_fmac_f32_e32 v6, v141, v225
	v_fmac_f32_e32 v7, v141, v229
	v_add_u32_e32 v27, 64, v27
	global_load_dword v126, v125, s[10:11]
	s_add_u32 s10, s10, 0x6000
	s_addc_u32 s11, s11, 0
	global_load_dword v127, v125, s[10:11]
	s_add_u32 s10, s10, 0x6000
	s_addc_u32 s11, s11, 0
	global_load_dword v128, v125, s[10:11]
	s_add_u32 s10, s10, 0x6000
	s_addc_u32 s11, s11, 0
	global_load_dword v129, v125, s[10:11]
	s_add_u32 s10, s10, 0x6000
	s_addc_u32 s11, s11, 0
	global_load_dword v130, v125, s[10:11]
	s_add_u32 s10, s10, 0x6000
	s_addc_u32 s11, s11, 0
	global_load_dword v131, v125, s[10:11]
	s_add_u32 s10, s10, 0x6000
	s_addc_u32 s11, s11, 0
	global_load_dword v132, v125, s[10:11]
	s_add_u32 s10, s10, 0x6000
	s_addc_u32 s11, s11, 0
	global_load_dword v133, v125, s[10:11]
	s_add_u32 s10, s10, 0x6000
	s_addc_u32 s11, s11, 0
	global_load_dword v134, v125, s[10:11]
	s_add_u32 s10, s10, 0x6000
	s_addc_u32 s11, s11, 0
	global_load_dword v135, v125, s[10:11]
	s_add_u32 s10, s10, 0x6000
	s_addc_u32 s11, s11, 0
	global_load_dword v136, v125, s[10:11]
	s_add_u32 s10, s10, 0x6000
	s_addc_u32 s11, s11, 0
	global_load_dword v137, v125, s[10:11]
	s_add_u32 s10, s10, 0x6000
	s_addc_u32 s11, s11, 0
	global_load_dword v138, v125, s[10:11]
	s_add_u32 s10, s10, 0x6000
	s_addc_u32 s11, s11, 0
	global_load_dword v139, v125, s[10:11]
	s_add_u32 s10, s10, 0x6000
	s_addc_u32 s11, s11, 0
	global_load_dword v140, v125, s[10:11]
	s_add_u32 s10, s10, 0x6000
	s_addc_u32 s11, s11, 0
	global_load_dword v141, v125, s[10:11]
	s_add_u32 s10, s10, 0x6000
	s_addc_u32 s11, s11, 0
	ds_read_b128 v[28:31], v27 offset:0
	ds_read_b128 v[32:35], v27 offset:4096
	ds_read_b128 v[36:39], v27 offset:8192
	ds_read_b128 v[40:43], v27 offset:12288
	ds_read_b128 v[44:47], v27 offset:16384
	ds_read_b128 v[48:51], v27 offset:20480
	ds_read_b128 v[52:55], v27 offset:24576
	ds_read_b128 v[56:59], v27 offset:28672
	ds_read_b128 v[60:63], v27 offset:32768
	ds_read_b128 v[64:67], v27 offset:36864
	ds_read_b128 v[68:71], v27 offset:40960
	ds_read_b128 v[72:75], v27 offset:45056
	ds_read_b128 v[182:185], v27 offset:16
	ds_read_b128 v[186:189], v27 offset:4112
	ds_read_b128 v[190:193], v27 offset:8208
	ds_read_b128 v[194:197], v27 offset:12304
	ds_read_b128 v[198:201], v27 offset:16400
	ds_read_b128 v[202:205], v27 offset:20496
	ds_read_b128 v[206:209], v27 offset:24592
	ds_read_b128 v[210:213], v27 offset:28688
	ds_read_b128 v[214:217], v27 offset:32784
	ds_read_b128 v[218:221], v27 offset:36880
	ds_read_b128 v[222:225], v27 offset:40976
	ds_read_b128 v[226:229], v27 offset:45072
	s_waitcnt vmcnt(28)
	s_waitcnt lgkmcnt(12)
	v_fmac_f32_e32 v8, v142, v28
	v_fmac_f32_e32 v9, v142, v32
	v_fmac_f32_e32 v10, v142, v36
	v_fmac_f32_e32 v11, v142, v40
	v_fmac_f32_e32 v12, v142, v44
	v_fmac_f32_e32 v13, v142, v48
	v_fmac_f32_e32 v14, v142, v52
	v_fmac_f32_e32 v15, v142, v56
	v_fmac_f32_e32 v16, v142, v60
	v_fmac_f32_e32 v17, v142, v64
	v_fmac_f32_e32 v6, v142, v68
	v_fmac_f32_e32 v7, v142, v72
	v_fmac_f32_e32 v8, v143, v29
	v_fmac_f32_e32 v9, v143, v33
	v_fmac_f32_e32 v10, v143, v37
	v_fmac_f32_e32 v11, v143, v41
	v_fmac_f32_e32 v12, v143, v45
	v_fmac_f32_e32 v13, v143, v49
	v_fmac_f32_e32 v14, v143, v53
	v_fmac_f32_e32 v15, v143, v57
	v_fmac_f32_e32 v16, v143, v61
	v_fmac_f32_e32 v17, v143, v65
	v_fmac_f32_e32 v6, v143, v69
	v_fmac_f32_e32 v7, v143, v73
	v_fmac_f32_e32 v8, v144, v30
	v_fmac_f32_e32 v9, v144, v34
	v_fmac_f32_e32 v10, v144, v38
	v_fmac_f32_e32 v11, v144, v42
	v_fmac_f32_e32 v12, v144, v46
	v_fmac_f32_e32 v13, v144, v50
	v_fmac_f32_e32 v14, v144, v54
	v_fmac_f32_e32 v15, v144, v58
	v_fmac_f32_e32 v16, v144, v62
	v_fmac_f32_e32 v17, v144, v66
	v_fmac_f32_e32 v6, v144, v70
	v_fmac_f32_e32 v7, v144, v74
	v_fmac_f32_e32 v8, v145, v31
	v_fmac_f32_e32 v9, v145, v35
	v_fmac_f32_e32 v10, v145, v39
	v_fmac_f32_e32 v11, v145, v43
	v_fmac_f32_e32 v12, v145, v47
	v_fmac_f32_e32 v13, v145, v51
	v_fmac_f32_e32 v14, v145, v55
	v_fmac_f32_e32 v15, v145, v59
	v_fmac_f32_e32 v16, v145, v63
	v_fmac_f32_e32 v17, v145, v67
	v_fmac_f32_e32 v6, v145, v71
	v_fmac_f32_e32 v7, v145, v75
	ds_read_b128 v[28:31], v27 offset:32
	ds_read_b128 v[32:35], v27 offset:4128
	ds_read_b128 v[36:39], v27 offset:8224
	ds_read_b128 v[40:43], v27 offset:12320
	ds_read_b128 v[44:47], v27 offset:16416
	ds_read_b128 v[48:51], v27 offset:20512
	ds_read_b128 v[52:55], v27 offset:24608
	ds_read_b128 v[56:59], v27 offset:28704
	ds_read_b128 v[60:63], v27 offset:32800
	ds_read_b128 v[64:67], v27 offset:36896
	ds_read_b128 v[68:71], v27 offset:40992
	ds_read_b128 v[72:75], v27 offset:45088
	s_waitcnt vmcnt(24)
	s_waitcnt lgkmcnt(12)
	v_fmac_f32_e32 v8, v146, v182
	v_fmac_f32_e32 v9, v146, v186
	v_fmac_f32_e32 v10, v146, v190
	v_fmac_f32_e32 v11, v146, v194
	v_fmac_f32_e32 v12, v146, v198
	v_fmac_f32_e32 v13, v146, v202
	v_fmac_f32_e32 v14, v146, v206
	v_fmac_f32_e32 v15, v146, v210
	v_fmac_f32_e32 v16, v146, v214
	v_fmac_f32_e32 v17, v146, v218
	v_fmac_f32_e32 v6, v146, v222
	v_fmac_f32_e32 v7, v146, v226
	v_fmac_f32_e32 v8, v147, v183
	v_fmac_f32_e32 v9, v147, v187
	v_fmac_f32_e32 v10, v147, v191
	v_fmac_f32_e32 v11, v147, v195
	v_fmac_f32_e32 v12, v147, v199
	v_fmac_f32_e32 v13, v147, v203
	v_fmac_f32_e32 v14, v147, v207
	v_fmac_f32_e32 v15, v147, v211
	v_fmac_f32_e32 v16, v147, v215
	v_fmac_f32_e32 v17, v147, v219
	v_fmac_f32_e32 v6, v147, v223
	v_fmac_f32_e32 v7, v147, v227
	v_fmac_f32_e32 v8, v148, v184
	v_fmac_f32_e32 v9, v148, v188
	v_fmac_f32_e32 v10, v148, v192
	v_fmac_f32_e32 v11, v148, v196
	v_fmac_f32_e32 v12, v148, v200
	v_fmac_f32_e32 v13, v148, v204
	v_fmac_f32_e32 v14, v148, v208
	v_fmac_f32_e32 v15, v148, v212
	v_fmac_f32_e32 v16, v148, v216
	v_fmac_f32_e32 v17, v148, v220
	v_fmac_f32_e32 v6, v148, v224
	v_fmac_f32_e32 v7, v148, v228
	v_fmac_f32_e32 v8, v149, v185
	v_fmac_f32_e32 v9, v149, v189
	v_fmac_f32_e32 v10, v149, v193
	v_fmac_f32_e32 v11, v149, v197
	v_fmac_f32_e32 v12, v149, v201
	v_fmac_f32_e32 v13, v149, v205
	v_fmac_f32_e32 v14, v149, v209
	v_fmac_f32_e32 v15, v149, v213
	v_fmac_f32_e32 v16, v149, v217
	v_fmac_f32_e32 v17, v149, v221
	v_fmac_f32_e32 v6, v149, v225
	v_fmac_f32_e32 v7, v149, v229
	ds_read_b128 v[182:185], v27 offset:48
	ds_read_b128 v[186:189], v27 offset:4144
	ds_read_b128 v[190:193], v27 offset:8240
	ds_read_b128 v[194:197], v27 offset:12336
	ds_read_b128 v[198:201], v27 offset:16432
	ds_read_b128 v[202:205], v27 offset:20528
	ds_read_b128 v[206:209], v27 offset:24624
	ds_read_b128 v[210:213], v27 offset:28720
	ds_read_b128 v[214:217], v27 offset:32816
	ds_read_b128 v[218:221], v27 offset:36912
	ds_read_b128 v[222:225], v27 offset:41008
	ds_read_b128 v[226:229], v27 offset:45104
	s_waitcnt vmcnt(20)
	s_waitcnt lgkmcnt(12)
	v_fmac_f32_e32 v8, v150, v28
	v_fmac_f32_e32 v9, v150, v32
	v_fmac_f32_e32 v10, v150, v36
	v_fmac_f32_e32 v11, v150, v40
	v_fmac_f32_e32 v12, v150, v44
	v_fmac_f32_e32 v13, v150, v48
	v_fmac_f32_e32 v14, v150, v52
	v_fmac_f32_e32 v15, v150, v56
	v_fmac_f32_e32 v16, v150, v60
	v_fmac_f32_e32 v17, v150, v64
	v_fmac_f32_e32 v6, v150, v68
	v_fmac_f32_e32 v7, v150, v72
	v_fmac_f32_e32 v8, v151, v29
	v_fmac_f32_e32 v9, v151, v33
	v_fmac_f32_e32 v10, v151, v37
	v_fmac_f32_e32 v11, v151, v41
	v_fmac_f32_e32 v12, v151, v45
	v_fmac_f32_e32 v13, v151, v49
	v_fmac_f32_e32 v14, v151, v53
	v_fmac_f32_e32 v15, v151, v57
	v_fmac_f32_e32 v16, v151, v61
	v_fmac_f32_e32 v17, v151, v65
	v_fmac_f32_e32 v6, v151, v69
	v_fmac_f32_e32 v7, v151, v73
	v_fmac_f32_e32 v8, v152, v30
	v_fmac_f32_e32 v9, v152, v34
	v_fmac_f32_e32 v10, v152, v38
	v_fmac_f32_e32 v11, v152, v42
	v_fmac_f32_e32 v12, v152, v46
	v_fmac_f32_e32 v13, v152, v50
	v_fmac_f32_e32 v14, v152, v54
	v_fmac_f32_e32 v15, v152, v58
	v_fmac_f32_e32 v16, v152, v62
	v_fmac_f32_e32 v17, v152, v66
	v_fmac_f32_e32 v6, v152, v70
	v_fmac_f32_e32 v7, v152, v74
	v_fmac_f32_e32 v8, v153, v31
	v_fmac_f32_e32 v9, v153, v35
	v_fmac_f32_e32 v10, v153, v39
	v_fmac_f32_e32 v11, v153, v43
	v_fmac_f32_e32 v12, v153, v47
	v_fmac_f32_e32 v13, v153, v51
	v_fmac_f32_e32 v14, v153, v55
	v_fmac_f32_e32 v15, v153, v59
	v_fmac_f32_e32 v16, v153, v63
	v_fmac_f32_e32 v17, v153, v67
	v_fmac_f32_e32 v6, v153, v71
	v_fmac_f32_e32 v7, v153, v75
	s_waitcnt vmcnt(16)
	s_waitcnt lgkmcnt(0)
	v_fmac_f32_e32 v8, v154, v182
	v_fmac_f32_e32 v9, v154, v186
	v_fmac_f32_e32 v10, v154, v190
	v_fmac_f32_e32 v11, v154, v194
	v_fmac_f32_e32 v12, v154, v198
	v_fmac_f32_e32 v13, v154, v202
	v_fmac_f32_e32 v14, v154, v206
	v_fmac_f32_e32 v15, v154, v210
	v_fmac_f32_e32 v16, v154, v214
	v_fmac_f32_e32 v17, v154, v218
	v_fmac_f32_e32 v6, v154, v222
	v_fmac_f32_e32 v7, v154, v226
	v_fmac_f32_e32 v8, v155, v183
	v_fmac_f32_e32 v9, v155, v187
	v_fmac_f32_e32 v10, v155, v191
	v_fmac_f32_e32 v11, v155, v195
	v_fmac_f32_e32 v12, v155, v199
	v_fmac_f32_e32 v13, v155, v203
	v_fmac_f32_e32 v14, v155, v207
	v_fmac_f32_e32 v15, v155, v211
	v_fmac_f32_e32 v16, v155, v215
	v_fmac_f32_e32 v17, v155, v219
	v_fmac_f32_e32 v6, v155, v223
	v_fmac_f32_e32 v7, v155, v227
	v_fmac_f32_e32 v8, v156, v184
	v_fmac_f32_e32 v9, v156, v188
	v_fmac_f32_e32 v10, v156, v192
	v_fmac_f32_e32 v11, v156, v196
	v_fmac_f32_e32 v12, v156, v200
	v_fmac_f32_e32 v13, v156, v204
	v_fmac_f32_e32 v14, v156, v208
	v_fmac_f32_e32 v15, v156, v212
	v_fmac_f32_e32 v16, v156, v216
	v_fmac_f32_e32 v17, v156, v220
	v_fmac_f32_e32 v6, v156, v224
	v_fmac_f32_e32 v7, v156, v228
	v_fmac_f32_e32 v8, v157, v185
	v_fmac_f32_e32 v9, v157, v189
	v_fmac_f32_e32 v10, v157, v193
	v_fmac_f32_e32 v11, v157, v197
	v_fmac_f32_e32 v12, v157, v201
	v_fmac_f32_e32 v13, v157, v205
	v_fmac_f32_e32 v14, v157, v209
	v_fmac_f32_e32 v15, v157, v213
	v_fmac_f32_e32 v16, v157, v217
	v_fmac_f32_e32 v17, v157, v221
	v_fmac_f32_e32 v6, v157, v225
	v_fmac_f32_e32 v7, v157, v229
	v_add_u32_e32 v27, 64, v27
	global_load_dword v142, v125, s[10:11]
	s_add_u32 s10, s10, 0x6000
	s_addc_u32 s11, s11, 0
	global_load_dword v143, v125, s[10:11]
	s_add_u32 s10, s10, 0x6000
	s_addc_u32 s11, s11, 0
	global_load_dword v144, v125, s[10:11]
	s_add_u32 s10, s10, 0x6000
	s_addc_u32 s11, s11, 0
	global_load_dword v145, v125, s[10:11]
	s_add_u32 s10, s10, 0x6000
	s_addc_u32 s11, s11, 0
	global_load_dword v146, v125, s[10:11]
	s_add_u32 s10, s10, 0x6000
	s_addc_u32 s11, s11, 0
	global_load_dword v147, v125, s[10:11]
	s_add_u32 s10, s10, 0x6000
	s_addc_u32 s11, s11, 0
	global_load_dword v148, v125, s[10:11]
	s_add_u32 s10, s10, 0x6000
	s_addc_u32 s11, s11, 0
	global_load_dword v149, v125, s[10:11]
	s_add_u32 s10, s10, 0x6000
	s_addc_u32 s11, s11, 0
	global_load_dword v150, v125, s[10:11]
	s_add_u32 s10, s10, 0x6000
	s_addc_u32 s11, s11, 0
	global_load_dword v151, v125, s[10:11]
	s_add_u32 s10, s10, 0x6000
	s_addc_u32 s11, s11, 0
	global_load_dword v152, v125, s[10:11]
	s_add_u32 s10, s10, 0x6000
	s_addc_u32 s11, s11, 0
	global_load_dword v153, v125, s[10:11]
	s_add_u32 s10, s10, 0x6000
	s_addc_u32 s11, s11, 0
	global_load_dword v154, v125, s[10:11]
	s_add_u32 s10, s10, 0x6000
	s_addc_u32 s11, s11, 0
	global_load_dword v155, v125, s[10:11]
	s_add_u32 s10, s10, 0x6000
	s_addc_u32 s11, s11, 0
	global_load_dword v156, v125, s[10:11]
	s_add_u32 s10, s10, 0x6000
	s_addc_u32 s11, s11, 0
	global_load_dword v157, v125, s[10:11]
	s_add_u32 s10, s10, 0x6000
	s_addc_u32 s11, s11, 0
	s_sub_u32 s8, s8, 1
	s_cmp_lg_u32 s8, 0
	s_cbranch_scc1 .Lada_loop
	ds_read_b128 v[28:31], v27 offset:0
	ds_read_b128 v[32:35], v27 offset:4096
	ds_read_b128 v[36:39], v27 offset:8192
	ds_read_b128 v[40:43], v27 offset:12288
	ds_read_b128 v[44:47], v27 offset:16384
	ds_read_b128 v[48:51], v27 offset:20480
	ds_read_b128 v[52:55], v27 offset:24576
	ds_read_b128 v[56:59], v27 offset:28672
	ds_read_b128 v[60:63], v27 offset:32768
	ds_read_b128 v[64:67], v27 offset:36864
	ds_read_b128 v[68:71], v27 offset:40960
	ds_read_b128 v[72:75], v27 offset:45056
	ds_read_b128 v[182:185], v27 offset:16
	ds_read_b128 v[186:189], v27 offset:4112
	ds_read_b128 v[190:193], v27 offset:8208
	ds_read_b128 v[194:197], v27 offset:12304
	ds_read_b128 v[198:201], v27 offset:16400
	ds_read_b128 v[202:205], v27 offset:20496
	ds_read_b128 v[206:209], v27 offset:24592
	ds_read_b128 v[210:213], v27 offset:28688
	ds_read_b128 v[214:217], v27 offset:32784
	ds_read_b128 v[218:221], v27 offset:36880
	ds_read_b128 v[222:225], v27 offset:40976
	ds_read_b128 v[226:229], v27 offset:45072
	s_waitcnt vmcnt(28)
	s_waitcnt lgkmcnt(12)
	v_fmac_f32_e32 v8, v126, v28
	v_fmac_f32_e32 v9, v126, v32
	v_fmac_f32_e32 v10, v126, v36
	v_fmac_f32_e32 v11, v126, v40
	v_fmac_f32_e32 v12, v126, v44
	v_fmac_f32_e32 v13, v126, v48
	v_fmac_f32_e32 v14, v126, v52
	v_fmac_f32_e32 v15, v126, v56
	v_fmac_f32_e32 v16, v126, v60
	v_fmac_f32_e32 v17, v126, v64
	v_fmac_f32_e32 v6, v126, v68
	v_fmac_f32_e32 v7, v126, v72
	v_fmac_f32_e32 v8, v127, v29
	v_fmac_f32_e32 v9, v127, v33
	v_fmac_f32_e32 v10, v127, v37
	v_fmac_f32_e32 v11, v127, v41
	v_fmac_f32_e32 v12, v127, v45
	v_fmac_f32_e32 v13, v127, v49
	v_fmac_f32_e32 v14, v127, v53
	v_fmac_f32_e32 v15, v127, v57
	v_fmac_f32_e32 v16, v127, v61
	v_fmac_f32_e32 v17, v127, v65
	v_fmac_f32_e32 v6, v127, v69
	v_fmac_f32_e32 v7, v127, v73
	v_fmac_f32_e32 v8, v128, v30
	v_fmac_f32_e32 v9, v128, v34
	v_fmac_f32_e32 v10, v128, v38
	v_fmac_f32_e32 v11, v128, v42
	v_fmac_f32_e32 v12, v128, v46
	v_fmac_f32_e32 v13, v128, v50
	v_fmac_f32_e32 v14, v128, v54
	v_fmac_f32_e32 v15, v128, v58
	v_fmac_f32_e32 v16, v128, v62
	v_fmac_f32_e32 v17, v128, v66
	v_fmac_f32_e32 v6, v128, v70
	v_fmac_f32_e32 v7, v128, v74
	v_fmac_f32_e32 v8, v129, v31
	v_fmac_f32_e32 v9, v129, v35
	v_fmac_f32_e32 v10, v129, v39
	v_fmac_f32_e32 v11, v129, v43
	v_fmac_f32_e32 v12, v129, v47
	v_fmac_f32_e32 v13, v129, v51
	v_fmac_f32_e32 v14, v129, v55
	v_fmac_f32_e32 v15, v129, v59
	v_fmac_f32_e32 v16, v129, v63
	v_fmac_f32_e32 v17, v129, v67
	v_fmac_f32_e32 v6, v129, v71
	v_fmac_f32_e32 v7, v129, v75
	ds_read_b128 v[28:31], v27 offset:32
	ds_read_b128 v[32:35], v27 offset:4128
	ds_read_b128 v[36:39], v27 offset:8224
	ds_read_b128 v[40:43], v27 offset:12320
	ds_read_b128 v[44:47], v27 offset:16416
	ds_read_b128 v[48:51], v27 offset:20512
	ds_read_b128 v[52:55], v27 offset:24608
	ds_read_b128 v[56:59], v27 offset:28704
	ds_read_b128 v[60:63], v27 offset:32800
	ds_read_b128 v[64:67], v27 offset:36896
	ds_read_b128 v[68:71], v27 offset:40992
	ds_read_b128 v[72:75], v27 offset:45088
	s_waitcnt vmcnt(24)
	s_waitcnt lgkmcnt(12)
	v_fmac_f32_e32 v8, v130, v182
	v_fmac_f32_e32 v9, v130, v186
	v_fmac_f32_e32 v10, v130, v190
	v_fmac_f32_e32 v11, v130, v194
	v_fmac_f32_e32 v12, v130, v198
	v_fmac_f32_e32 v13, v130, v202
	v_fmac_f32_e32 v14, v130, v206
	v_fmac_f32_e32 v15, v130, v210
	v_fmac_f32_e32 v16, v130, v214
	v_fmac_f32_e32 v17, v130, v218
	v_fmac_f32_e32 v6, v130, v222
	v_fmac_f32_e32 v7, v130, v226
	v_fmac_f32_e32 v8, v131, v183
	v_fmac_f32_e32 v9, v131, v187
	v_fmac_f32_e32 v10, v131, v191
	v_fmac_f32_e32 v11, v131, v195
	v_fmac_f32_e32 v12, v131, v199
	v_fmac_f32_e32 v13, v131, v203
	v_fmac_f32_e32 v14, v131, v207
	v_fmac_f32_e32 v15, v131, v211
	v_fmac_f32_e32 v16, v131, v215
	v_fmac_f32_e32 v17, v131, v219
	v_fmac_f32_e32 v6, v131, v223
	v_fmac_f32_e32 v7, v131, v227
	v_fmac_f32_e32 v8, v132, v184
	v_fmac_f32_e32 v9, v132, v188
	v_fmac_f32_e32 v10, v132, v192
	v_fmac_f32_e32 v11, v132, v196
	v_fmac_f32_e32 v12, v132, v200
	v_fmac_f32_e32 v13, v132, v204
	v_fmac_f32_e32 v14, v132, v208
	v_fmac_f32_e32 v15, v132, v212
	v_fmac_f32_e32 v16, v132, v216
	v_fmac_f32_e32 v17, v132, v220
	v_fmac_f32_e32 v6, v132, v224
	v_fmac_f32_e32 v7, v132, v228
	v_fmac_f32_e32 v8, v133, v185
	v_fmac_f32_e32 v9, v133, v189
	v_fmac_f32_e32 v10, v133, v193
	v_fmac_f32_e32 v11, v133, v197
	v_fmac_f32_e32 v12, v133, v201
	v_fmac_f32_e32 v13, v133, v205
	v_fmac_f32_e32 v14, v133, v209
	v_fmac_f32_e32 v15, v133, v213
	v_fmac_f32_e32 v16, v133, v217
	v_fmac_f32_e32 v17, v133, v221
	v_fmac_f32_e32 v6, v133, v225
	v_fmac_f32_e32 v7, v133, v229
	ds_read_b128 v[182:185], v27 offset:48
	ds_read_b128 v[186:189], v27 offset:4144
	ds_read_b128 v[190:193], v27 offset:8240
	ds_read_b128 v[194:197], v27 offset:12336
	ds_read_b128 v[198:201], v27 offset:16432
	ds_read_b128 v[202:205], v27 offset:20528
	ds_read_b128 v[206:209], v27 offset:24624
	ds_read_b128 v[210:213], v27 offset:28720
	ds_read_b128 v[214:217], v27 offset:32816
	ds_read_b128 v[218:221], v27 offset:36912
	ds_read_b128 v[222:225], v27 offset:41008
	ds_read_b128 v[226:229], v27 offset:45104
	s_waitcnt vmcnt(20)
	s_waitcnt lgkmcnt(12)
	v_fmac_f32_e32 v8, v134, v28
	v_fmac_f32_e32 v9, v134, v32
	v_fmac_f32_e32 v10, v134, v36
	v_fmac_f32_e32 v11, v134, v40
	v_fmac_f32_e32 v12, v134, v44
	v_fmac_f32_e32 v13, v134, v48
	v_fmac_f32_e32 v14, v134, v52
	v_fmac_f32_e32 v15, v134, v56
	v_fmac_f32_e32 v16, v134, v60
	v_fmac_f32_e32 v17, v134, v64
	v_fmac_f32_e32 v6, v134, v68
	v_fmac_f32_e32 v7, v134, v72
	v_fmac_f32_e32 v8, v135, v29
	v_fmac_f32_e32 v9, v135, v33
	v_fmac_f32_e32 v10, v135, v37
	v_fmac_f32_e32 v11, v135, v41
	v_fmac_f32_e32 v12, v135, v45
	v_fmac_f32_e32 v13, v135, v49
	v_fmac_f32_e32 v14, v135, v53
	v_fmac_f32_e32 v15, v135, v57
	v_fmac_f32_e32 v16, v135, v61
	v_fmac_f32_e32 v17, v135, v65
	v_fmac_f32_e32 v6, v135, v69
	v_fmac_f32_e32 v7, v135, v73
	v_fmac_f32_e32 v8, v136, v30
	v_fmac_f32_e32 v9, v136, v34
	v_fmac_f32_e32 v10, v136, v38
	v_fmac_f32_e32 v11, v136, v42
	v_fmac_f32_e32 v12, v136, v46
	v_fmac_f32_e32 v13, v136, v50
	v_fmac_f32_e32 v14, v136, v54
	v_fmac_f32_e32 v15, v136, v58
	v_fmac_f32_e32 v16, v136, v62
	v_fmac_f32_e32 v17, v136, v66
	v_fmac_f32_e32 v6, v136, v70
	v_fmac_f32_e32 v7, v136, v74
	v_fmac_f32_e32 v8, v137, v31
	v_fmac_f32_e32 v9, v137, v35
	v_fmac_f32_e32 v10, v137, v39
	v_fmac_f32_e32 v11, v137, v43
	v_fmac_f32_e32 v12, v137, v47
	v_fmac_f32_e32 v13, v137, v51
	v_fmac_f32_e32 v14, v137, v55
	v_fmac_f32_e32 v15, v137, v59
	v_fmac_f32_e32 v16, v137, v63
	v_fmac_f32_e32 v17, v137, v67
	v_fmac_f32_e32 v6, v137, v71
	v_fmac_f32_e32 v7, v137, v75
	s_waitcnt vmcnt(16)
	s_waitcnt lgkmcnt(0)
	v_fmac_f32_e32 v8, v138, v182
	v_fmac_f32_e32 v9, v138, v186
	v_fmac_f32_e32 v10, v138, v190
	v_fmac_f32_e32 v11, v138, v194
	v_fmac_f32_e32 v12, v138, v198
	v_fmac_f32_e32 v13, v138, v202
	v_fmac_f32_e32 v14, v138, v206
	v_fmac_f32_e32 v15, v138, v210
	v_fmac_f32_e32 v16, v138, v214
	v_fmac_f32_e32 v17, v138, v218
	v_fmac_f32_e32 v6, v138, v222
	v_fmac_f32_e32 v7, v138, v226
	v_fmac_f32_e32 v8, v139, v183
	v_fmac_f32_e32 v9, v139, v187
	v_fmac_f32_e32 v10, v139, v191
	v_fmac_f32_e32 v11, v139, v195
	v_fmac_f32_e32 v12, v139, v199
	v_fmac_f32_e32 v13, v139, v203
	v_fmac_f32_e32 v14, v139, v207
	v_fmac_f32_e32 v15, v139, v211
	v_fmac_f32_e32 v16, v139, v215
	v_fmac_f32_e32 v17, v139, v219
	v_fmac_f32_e32 v6, v139, v223
	v_fmac_f32_e32 v7, v139, v227
	v_fmac_f32_e32 v8, v140, v184
	v_fmac_f32_e32 v9, v140, v188
	v_fmac_f32_e32 v10, v140, v192
	v_fmac_f32_e32 v11, v140, v196
	v_fmac_f32_e32 v12, v140, v200
	v_fmac_f32_e32 v13, v140, v204
	v_fmac_f32_e32 v14, v140, v208
	v_fmac_f32_e32 v15, v140, v212
	v_fmac_f32_e32 v16, v140, v216
	v_fmac_f32_e32 v17, v140, v220
	v_fmac_f32_e32 v6, v140, v224
	v_fmac_f32_e32 v7, v140, v228
	v_fmac_f32_e32 v8, v141, v185
	v_fmac_f32_e32 v9, v141, v189
	v_fmac_f32_e32 v10, v141, v193
	v_fmac_f32_e32 v11, v141, v197
	v_fmac_f32_e32 v12, v141, v201
	v_fmac_f32_e32 v13, v141, v205
	v_fmac_f32_e32 v14, v141, v209
	v_fmac_f32_e32 v15, v141, v213
	v_fmac_f32_e32 v16, v141, v217
	v_fmac_f32_e32 v17, v141, v221
	v_fmac_f32_e32 v6, v141, v225
	v_fmac_f32_e32 v7, v141, v229
	v_add_u32_e32 v27, 64, v27
	ds_read_b128 v[28:31], v27 offset:0
	ds_read_b128 v[32:35], v27 offset:4096
	ds_read_b128 v[36:39], v27 offset:8192
	ds_read_b128 v[40:43], v27 offset:12288
	ds_read_b128 v[44:47], v27 offset:16384
	ds_read_b128 v[48:51], v27 offset:20480
	ds_read_b128 v[52:55], v27 offset:24576
	ds_read_b128 v[56:59], v27 offset:28672
	ds_read_b128 v[60:63], v27 offset:32768
	ds_read_b128 v[64:67], v27 offset:36864
	ds_read_b128 v[68:71], v27 offset:40960
	ds_read_b128 v[72:75], v27 offset:45056
	ds_read_b128 v[182:185], v27 offset:16
	ds_read_b128 v[186:189], v27 offset:4112
	ds_read_b128 v[190:193], v27 offset:8208
	ds_read_b128 v[194:197], v27 offset:12304
	ds_read_b128 v[198:201], v27 offset:16400
	ds_read_b128 v[202:205], v27 offset:20496
	ds_read_b128 v[206:209], v27 offset:24592
	ds_read_b128 v[210:213], v27 offset:28688
	ds_read_b128 v[214:217], v27 offset:32784
	ds_read_b128 v[218:221], v27 offset:36880
	ds_read_b128 v[222:225], v27 offset:40976
	ds_read_b128 v[226:229], v27 offset:45072
	s_waitcnt vmcnt(12)
	s_waitcnt lgkmcnt(12)
	v_fmac_f32_e32 v8, v142, v28
	v_fmac_f32_e32 v9, v142, v32
	v_fmac_f32_e32 v10, v142, v36
	v_fmac_f32_e32 v11, v142, v40
	v_fmac_f32_e32 v12, v142, v44
	v_fmac_f32_e32 v13, v142, v48
	v_fmac_f32_e32 v14, v142, v52
	v_fmac_f32_e32 v15, v142, v56
	v_fmac_f32_e32 v16, v142, v60
	v_fmac_f32_e32 v17, v142, v64
	v_fmac_f32_e32 v6, v142, v68
	v_fmac_f32_e32 v7, v142, v72
	v_fmac_f32_e32 v8, v143, v29
	v_fmac_f32_e32 v9, v143, v33
	v_fmac_f32_e32 v10, v143, v37
	v_fmac_f32_e32 v11, v143, v41
	v_fmac_f32_e32 v12, v143, v45
	v_fmac_f32_e32 v13, v143, v49
	v_fmac_f32_e32 v14, v143, v53
	v_fmac_f32_e32 v15, v143, v57
	v_fmac_f32_e32 v16, v143, v61
	v_fmac_f32_e32 v17, v143, v65
	v_fmac_f32_e32 v6, v143, v69
	v_fmac_f32_e32 v7, v143, v73
	v_fmac_f32_e32 v8, v144, v30
	v_fmac_f32_e32 v9, v144, v34
	v_fmac_f32_e32 v10, v144, v38
	v_fmac_f32_e32 v11, v144, v42
	v_fmac_f32_e32 v12, v144, v46
	v_fmac_f32_e32 v13, v144, v50
	v_fmac_f32_e32 v14, v144, v54
	v_fmac_f32_e32 v15, v144, v58
	v_fmac_f32_e32 v16, v144, v62
	v_fmac_f32_e32 v17, v144, v66
	v_fmac_f32_e32 v6, v144, v70
	v_fmac_f32_e32 v7, v144, v74
	v_fmac_f32_e32 v8, v145, v31
	v_fmac_f32_e32 v9, v145, v35
	v_fmac_f32_e32 v10, v145, v39
	v_fmac_f32_e32 v11, v145, v43
	v_fmac_f32_e32 v12, v145, v47
	v_fmac_f32_e32 v13, v145, v51
	v_fmac_f32_e32 v14, v145, v55
	v_fmac_f32_e32 v15, v145, v59
	v_fmac_f32_e32 v16, v145, v63
	v_fmac_f32_e32 v17, v145, v67
	v_fmac_f32_e32 v6, v145, v71
	v_fmac_f32_e32 v7, v145, v75
	ds_read_b128 v[28:31], v27 offset:32
	ds_read_b128 v[32:35], v27 offset:4128
	ds_read_b128 v[36:39], v27 offset:8224
	ds_read_b128 v[40:43], v27 offset:12320
	ds_read_b128 v[44:47], v27 offset:16416
	ds_read_b128 v[48:51], v27 offset:20512
	ds_read_b128 v[52:55], v27 offset:24608
	ds_read_b128 v[56:59], v27 offset:28704
	ds_read_b128 v[60:63], v27 offset:32800
	ds_read_b128 v[64:67], v27 offset:36896
	ds_read_b128 v[68:71], v27 offset:40992
	ds_read_b128 v[72:75], v27 offset:45088
	s_waitcnt vmcnt(8)
	s_waitcnt lgkmcnt(12)
	v_fmac_f32_e32 v8, v146, v182
	v_fmac_f32_e32 v9, v146, v186
	v_fmac_f32_e32 v10, v146, v190
	v_fmac_f32_e32 v11, v146, v194
	v_fmac_f32_e32 v12, v146, v198
	v_fmac_f32_e32 v13, v146, v202
	v_fmac_f32_e32 v14, v146, v206
	v_fmac_f32_e32 v15, v146, v210
	v_fmac_f32_e32 v16, v146, v214
	v_fmac_f32_e32 v17, v146, v218
	v_fmac_f32_e32 v6, v146, v222
	v_fmac_f32_e32 v7, v146, v226
	v_fmac_f32_e32 v8, v147, v183
	v_fmac_f32_e32 v9, v147, v187
	v_fmac_f32_e32 v10, v147, v191
	v_fmac_f32_e32 v11, v147, v195
	v_fmac_f32_e32 v12, v147, v199
	v_fmac_f32_e32 v13, v147, v203
	v_fmac_f32_e32 v14, v147, v207
	v_fmac_f32_e32 v15, v147, v211
	v_fmac_f32_e32 v16, v147, v215
	v_fmac_f32_e32 v17, v147, v219
	v_fmac_f32_e32 v6, v147, v223
	v_fmac_f32_e32 v7, v147, v227
	v_fmac_f32_e32 v8, v148, v184
	v_fmac_f32_e32 v9, v148, v188
	v_fmac_f32_e32 v10, v148, v192
	v_fmac_f32_e32 v11, v148, v196
	v_fmac_f32_e32 v12, v148, v200
	v_fmac_f32_e32 v13, v148, v204
	v_fmac_f32_e32 v14, v148, v208
	v_fmac_f32_e32 v15, v148, v212
	v_fmac_f32_e32 v16, v148, v216
	v_fmac_f32_e32 v17, v148, v220
	v_fmac_f32_e32 v6, v148, v224
	v_fmac_f32_e32 v7, v148, v228
	v_fmac_f32_e32 v8, v149, v185
	v_fmac_f32_e32 v9, v149, v189
	v_fmac_f32_e32 v10, v149, v193
	v_fmac_f32_e32 v11, v149, v197
	v_fmac_f32_e32 v12, v149, v201
	v_fmac_f32_e32 v13, v149, v205
	v_fmac_f32_e32 v14, v149, v209
	v_fmac_f32_e32 v15, v149, v213
	v_fmac_f32_e32 v16, v149, v217
	v_fmac_f32_e32 v17, v149, v221
	v_fmac_f32_e32 v6, v149, v225
	v_fmac_f32_e32 v7, v149, v229
	ds_read_b128 v[182:185], v27 offset:48
	ds_read_b128 v[186:189], v27 offset:4144
	ds_read_b128 v[190:193], v27 offset:8240
	ds_read_b128 v[194:197], v27 offset:12336
	ds_read_b128 v[198:201], v27 offset:16432
	ds_read_b128 v[202:205], v27 offset:20528
	ds_read_b128 v[206:209], v27 offset:24624
	ds_read_b128 v[210:213], v27 offset:28720
	ds_read_b128 v[214:217], v27 offset:32816
	ds_read_b128 v[218:221], v27 offset:36912
	ds_read_b128 v[222:225], v27 offset:41008
	ds_read_b128 v[226:229], v27 offset:45104
	s_waitcnt vmcnt(4)
	s_waitcnt lgkmcnt(12)
	v_fmac_f32_e32 v8, v150, v28
	v_fmac_f32_e32 v9, v150, v32
	v_fmac_f32_e32 v10, v150, v36
	v_fmac_f32_e32 v11, v150, v40
	v_fmac_f32_e32 v12, v150, v44
	v_fmac_f32_e32 v13, v150, v48
	v_fmac_f32_e32 v14, v150, v52
	v_fmac_f32_e32 v15, v150, v56
	v_fmac_f32_e32 v16, v150, v60
	v_fmac_f32_e32 v17, v150, v64
	v_fmac_f32_e32 v6, v150, v68
	v_fmac_f32_e32 v7, v150, v72
	v_fmac_f32_e32 v8, v151, v29
	v_fmac_f32_e32 v9, v151, v33
	v_fmac_f32_e32 v10, v151, v37
	v_fmac_f32_e32 v11, v151, v41
	v_fmac_f32_e32 v12, v151, v45
	v_fmac_f32_e32 v13, v151, v49
	v_fmac_f32_e32 v14, v151, v53
	v_fmac_f32_e32 v15, v151, v57
	v_fmac_f32_e32 v16, v151, v61
	v_fmac_f32_e32 v17, v151, v65
	v_fmac_f32_e32 v6, v151, v69
	v_fmac_f32_e32 v7, v151, v73
	v_fmac_f32_e32 v8, v152, v30
	v_fmac_f32_e32 v9, v152, v34
	v_fmac_f32_e32 v10, v152, v38
	v_fmac_f32_e32 v11, v152, v42
	v_fmac_f32_e32 v12, v152, v46
	v_fmac_f32_e32 v13, v152, v50
	v_fmac_f32_e32 v14, v152, v54
	v_fmac_f32_e32 v15, v152, v58
	v_fmac_f32_e32 v16, v152, v62
	v_fmac_f32_e32 v17, v152, v66
	v_fmac_f32_e32 v6, v152, v70
	v_fmac_f32_e32 v7, v152, v74
	v_fmac_f32_e32 v8, v153, v31
	v_fmac_f32_e32 v9, v153, v35
	v_fmac_f32_e32 v10, v153, v39
	v_fmac_f32_e32 v11, v153, v43
	v_fmac_f32_e32 v12, v153, v47
	v_fmac_f32_e32 v13, v153, v51
	v_fmac_f32_e32 v14, v153, v55
	v_fmac_f32_e32 v15, v153, v59
	v_fmac_f32_e32 v16, v153, v63
	v_fmac_f32_e32 v17, v153, v67
	v_fmac_f32_e32 v6, v153, v71
	v_fmac_f32_e32 v7, v153, v75
	s_waitcnt vmcnt(0)
	s_waitcnt lgkmcnt(0)
	v_fmac_f32_e32 v8, v154, v182
	v_fmac_f32_e32 v9, v154, v186
	v_fmac_f32_e32 v10, v154, v190
	v_fmac_f32_e32 v11, v154, v194
	v_fmac_f32_e32 v12, v154, v198
	v_fmac_f32_e32 v13, v154, v202
	v_fmac_f32_e32 v14, v154, v206
	v_fmac_f32_e32 v15, v154, v210
	v_fmac_f32_e32 v16, v154, v214
	v_fmac_f32_e32 v17, v154, v218
	v_fmac_f32_e32 v6, v154, v222
	v_fmac_f32_e32 v7, v154, v226
	v_fmac_f32_e32 v8, v155, v183
	v_fmac_f32_e32 v9, v155, v187
	v_fmac_f32_e32 v10, v155, v191
	v_fmac_f32_e32 v11, v155, v195
	v_fmac_f32_e32 v12, v155, v199
	v_fmac_f32_e32 v13, v155, v203
	v_fmac_f32_e32 v14, v155, v207
	v_fmac_f32_e32 v15, v155, v211
	v_fmac_f32_e32 v16, v155, v215
	v_fmac_f32_e32 v17, v155, v219
	v_fmac_f32_e32 v6, v155, v223
	v_fmac_f32_e32 v7, v155, v227
	v_fmac_f32_e32 v8, v156, v184
	v_fmac_f32_e32 v9, v156, v188
	v_fmac_f32_e32 v10, v156, v192
	v_fmac_f32_e32 v11, v156, v196
	v_fmac_f32_e32 v12, v156, v200
	v_fmac_f32_e32 v13, v156, v204
	v_fmac_f32_e32 v14, v156, v208
	v_fmac_f32_e32 v15, v156, v212
	v_fmac_f32_e32 v16, v156, v216
	v_fmac_f32_e32 v17, v156, v220
	v_fmac_f32_e32 v6, v156, v224
	v_fmac_f32_e32 v7, v156, v228
	v_fmac_f32_e32 v8, v157, v185
	v_fmac_f32_e32 v9, v157, v189
	v_fmac_f32_e32 v10, v157, v193
	v_fmac_f32_e32 v11, v157, v197
	v_fmac_f32_e32 v12, v157, v201
	v_fmac_f32_e32 v13, v157, v205
	v_fmac_f32_e32 v14, v157, v209
	v_fmac_f32_e32 v15, v157, v213
	v_fmac_f32_e32 v16, v157, v217
	v_fmac_f32_e32 v17, v157, v221
	v_fmac_f32_e32 v6, v157, v225
	v_fmac_f32_e32 v7, v157, v229
	v_add_u32_e32 v27, 64, v27
	ds_write2st64_b32 v26, v8, v9 offset0:192 offset1:193
	ds_write2st64_b32 v26, v10, v11 offset0:194 offset1:195
	ds_write2st64_b32 v26, v12, v13 offset0:196 offset1:197
	ds_write2st64_b32 v26, v14, v15 offset0:198 offset1:199
	ds_write2st64_b32 v26, v16, v17 offset0:200 offset1:201
	ds_write2st64_b32 v26, v6, v7 offset0:202 offset1:203
	s_waitcnt lgkmcnt(0)
	s_barrier
	s_and_saveexec_b64 s[8:9], s[2:3]
	s_cbranch_execz .LBB0_20
	v_lshl_or_b32 v4, s20, 6, v180
	v_ashrrev_i32_e32 v5, 31, v4
	v_lshl_add_u64 v[4:5], v[4:5], 2, s[66:67]
	s_mov_b64 s[10:11], 0
	v_mov_b32_e32 v0, v21
	v_mov_b32_e32 v6, v20
	v_mov_b32_e32 v8, v19
